# phase-0 weight transposes: all 32 (64 with the norm scale) loads of an item issued before the LDS writes, counted waits; was 8-64 dependent round trips per item
# speedup vs baseline: 1.0174x; 1.0152x over previous
.Ltrin_tail:
	s_waitcnt lgkmcnt(0)
	ds_read2_b32 v[100:101], v44 offset0:33 offset1:41
	ds_read2_b32 v[102:103], v44 offset1:8
	v_ashrrev_i32_e32 v29, 31, v28
	ds_read2_b32 v[104:105], v44 offset0:66 offset1:74
	ds_read2_b32 v[106:107], v44 offset0:99 offset1:107
	ds_read2_b32 v[108:109], v44 offset0:132 offset1:140
	ds_read2_b32 v[110:111], v44 offset0:165 offset1:173
	ds_read2_b32 v[112:113], v44 offset0:198 offset1:206
	ds_read2_b32 v[114:115], v44 offset0:231 offset1:239
	v_lshl_add_u64 v[98:99], v[28:29], 1, v[14:15]
	s_waitcnt lgkmcnt(6)
	v_cvt_pk_bf16_f32 v28, v102, v100
	v_add_u32_e32 v100, v43, v95
	v_lshlrev_b32_e32 v2, 5, v2
	v_sub_u32_e32 v116, v100, v2
	v_ashrrev_i32_e32 v117, 31, v116
	v_lshlrev_b64 v[118:119], 11, v[116:117]
	s_waitcnt lgkmcnt(4)
	v_cvt_pk_bf16_f32 v29, v104, v106
	s_waitcnt lgkmcnt(2)
	v_cvt_pk_bf16_f32 v30, v108, v110
	s_waitcnt lgkmcnt(0)
	v_cvt_pk_bf16_f32 v31, v112, v114
	v_lshl_add_u64 v[118:119], v[98:99], 0, v[118:119]
	v_add_u32_e32 v100, 8, v116
	global_store_dwordx4 v[118:119], v[28:31], off
	v_add_u32_e32 v118, 16, v116
	v_ashrrev_i32_e32 v119, 31, v118
	v_cvt_pk_bf16_f32 v28, v103, v101
	v_ashrrev_i32_e32 v101, 31, v100
	v_lshlrev_b64 v[100:101], 11, v[100:101]
	v_cvt_pk_bf16_f32 v29, v105, v107
	v_cvt_pk_bf16_f32 v30, v109, v111
	v_cvt_pk_bf16_f32 v31, v113, v115
	v_lshl_add_u64 v[100:101], v[98:99], 0, v[100:101]
	global_store_dwordx4 v[100:101], v[28:31], off
	ds_read2_b32 v[100:101], v44 offset0:49 offset1:57
	ds_read2_b32 v[102:103], v44 offset0:16 offset1:24
	ds_read2_b32 v[104:105], v44 offset0:82 offset1:90
	ds_read2_b32 v[106:107], v44 offset0:115 offset1:123
	ds_read2_b32 v[108:109], v44 offset0:148 offset1:156
	ds_read2_b32 v[110:111], v44 offset0:181 offset1:189
	ds_read2_b32 v[112:113], v44 offset0:214 offset1:222
	ds_read2_b32 v[114:115], v44 offset0:247 offset1:255
	v_lshlrev_b64 v[118:119], 11, v[118:119]
	s_waitcnt lgkmcnt(6)
	v_cvt_pk_bf16_f32 v28, v102, v100
	s_waitcnt lgkmcnt(4)
	v_cvt_pk_bf16_f32 v29, v104, v106
	s_waitcnt lgkmcnt(2)
	v_cvt_pk_bf16_f32 v30, v108, v110
	s_waitcnt lgkmcnt(0)
	v_cvt_pk_bf16_f32 v31, v112, v114
	v_lshl_add_u64 v[118:119], v[98:99], 0, v[118:119]
	v_add_u32_e32 v100, 24, v116
	global_store_dwordx4 v[118:119], v[28:31], off
	s_nop 1
	v_cvt_pk_bf16_f32 v28, v103, v101
	v_ashrrev_i32_e32 v101, 31, v100
	v_lshlrev_b64 v[100:101], 11, v[100:101]
	v_cvt_pk_bf16_f32 v29, v105, v107
	v_cvt_pk_bf16_f32 v30, v109, v111
	v_cvt_pk_bf16_f32 v31, v113, v115
	v_lshl_add_u64 v[98:99], v[98:99], 0, v[100:101]
	global_store_dwordx4 v[98:99], v[28:31], off
	s_waitcnt lgkmcnt(0)

.LBB0_522:
	s_movk_i32 s20, 0x117f
	v_cmp_lt_i32_e32 vcc, s20, v97
	s_and_saveexec_b64 s[20:21], vcc
	s_xor_b64 s[42:43], exec, s[20:21]
	s_cbranch_execz .LBB0_605
	s_movk_i32 s20, 0x157f
	v_cmp_lt_u32_e32 vcc, s20, v97
	s_and_saveexec_b64 s[20:21], vcc
	s_xor_b64 s[38:39], exec, s[20:21]
	s_cbranch_execz .LBB0_537
	s_movk_i32 s20, 0x177f
	v_cmp_lt_u32_e32 vcc, s20, v97
	s_and_saveexec_b64 s[20:21], vcc
	s_xor_b64 s[44:45], exec, s[20:21]
	s_cbranch_execz .LBB0_534
	s_movk_i32 s20, 0x197f
	v_cmp_lt_u32_e32 vcc, s20, v97
	s_and_saveexec_b64 s[20:21], vcc
	s_xor_b64 s[46:47], exec, s[20:21]
	s_cbranch_execz .LBB0_531
	s_movk_i32 s20, 0x247f
	v_cmp_lt_u32_e32 vcc, s20, v97
	s_and_saveexec_b64 s[20:21], vcc
	s_xor_b64 s[48:49], exec, s[20:21]
	s_cbranch_execz .LBB0_528
	v_and_b32_e32 v2, 0x7fffffc0, v96
	v_and_b32_e32 v98, 0x3e0, v95
	v_add_u32_e32 v28, 0xffffb700, v2
	v_lshlrev_b32_e32 v2, 2, v98
	v_lshl_add_u64 v[30:31], v[16:17], 0, v[2:3]
	v_or_b32_e32 v2, v28, v32
	v_lshlrev_b64 v[100:101], 12, v[2:3]
	v_lshl_add_u64 v[100:101], v[30:31], 0, v[100:101]
	v_or_b32_e32 v2, v28, v35
	global_load_dword v120, v[100:101], off nt
	v_lshlrev_b64 v[100:101], 12, v[2:3]
	v_lshl_add_u64 v[100:101], v[30:31], 0, v[100:101]
	global_load_dword v121, v[100:101], off nt
	v_add_u32_e32 v99, v33, v34
	v_or_b32_e32 v2, v28, v36
	v_lshlrev_b64 v[100:101], 12, v[2:3]
	v_lshl_add_u64 v[100:101], v[30:31], 0, v[100:101]
	v_or_b32_e32 v2, v28, v38
	global_load_dword v122, v[100:101], off nt
	v_lshlrev_b64 v[100:101], 12, v[2:3]
	v_lshl_add_u64 v[100:101], v[30:31], 0, v[100:101]
	global_load_dword v123, v[100:101], off nt
	v_or_b32_e32 v2, v28, v39
	v_lshlrev_b64 v[100:101], 12, v[2:3]
	v_lshl_add_u64 v[100:101], v[30:31], 0, v[100:101]
	v_or_b32_e32 v2, v28, v41
	global_load_dword v124, v[100:101], off nt
	v_lshlrev_b64 v[100:101], 12, v[2:3]
	v_lshl_add_u64 v[100:101], v[30:31], 0, v[100:101]
	global_load_dword v125, v[100:101], off nt
	v_add_u32_e32 v99, 0x400, v99
	v_or_b32_e32 v2, v28, v42
	v_lshlrev_b64 v[100:101], 12, v[2:3]
	v_lshl_add_u64 v[100:101], v[30:31], 0, v[100:101]
	v_or_b32_e32 v2, v28, v58
	global_load_dword v126, v[100:101], off nt
	v_lshlrev_b64 v[100:101], 12, v[2:3]
	v_lshl_add_u64 v[100:101], v[30:31], 0, v[100:101]
	global_load_dword v127, v[100:101], off nt
	v_add_u32_e32 v99, v33, v57
	v_or_b32_e32 v2, v28, v59
	v_lshlrev_b64 v[100:101], 12, v[2:3]
	v_lshl_add_u64 v[100:101], v[30:31], 0, v[100:101]
	v_or_b32_e32 v2, v28, v61
	global_load_dword v128, v[100:101], off nt
	v_lshlrev_b64 v[100:101], 12, v[2:3]
	v_lshl_add_u64 v[100:101], v[30:31], 0, v[100:101]
	global_load_dword v129, v[100:101], off nt
	v_or_b32_e32 v2, v28, v62
	v_lshlrev_b64 v[100:101], 12, v[2:3]
	v_lshl_add_u64 v[100:101], v[30:31], 0, v[100:101]
	v_or_b32_e32 v2, v28, v64
	global_load_dword v130, v[100:101], off nt
	v_lshlrev_b64 v[100:101], 12, v[2:3]
	v_lshl_add_u64 v[100:101], v[30:31], 0, v[100:101]
	global_load_dword v131, v[100:101], off nt
	v_add_u32_e32 v99, 0x400, v99
	v_or_b32_e32 v2, v28, v65
	v_lshlrev_b64 v[100:101], 12, v[2:3]
	v_lshl_add_u64 v[100:101], v[30:31], 0, v[100:101]
	v_or_b32_e32 v2, v28, v67
	global_load_dword v132, v[100:101], off nt
	v_lshlrev_b64 v[100:101], 12, v[2:3]
	v_lshl_add_u64 v[100:101], v[30:31], 0, v[100:101]
	global_load_dword v133, v[100:101], off nt
	v_add_u32_e32 v99, v33, v66
	v_or_b32_e32 v2, v28, v68
	v_lshlrev_b64 v[100:101], 12, v[2:3]
	v_lshl_add_u64 v[100:101], v[30:31], 0, v[100:101]
	v_or_b32_e32 v2, v28, v70
	global_load_dword v134, v[100:101], off nt
	v_lshlrev_b64 v[100:101], 12, v[2:3]
	v_lshl_add_u64 v[100:101], v[30:31], 0, v[100:101]
	global_load_dword v135, v[100:101], off nt
	v_or_b32_e32 v2, v28, v71
	v_lshlrev_b64 v[100:101], 12, v[2:3]
	v_lshl_add_u64 v[100:101], v[30:31], 0, v[100:101]
	v_or_b32_e32 v2, v28, v73
	global_load_dword v136, v[100:101], off nt
	v_lshlrev_b64 v[100:101], 12, v[2:3]
	v_lshl_add_u64 v[100:101], v[30:31], 0, v[100:101]
	global_load_dword v137, v[100:101], off nt
	v_add_u32_e32 v99, 0x400, v99
	v_or_b32_e32 v2, v28, v74
	v_lshlrev_b64 v[100:101], 12, v[2:3]
	v_lshl_add_u64 v[100:101], v[30:31], 0, v[100:101]
	v_or_b32_e32 v2, v28, v76
	global_load_dword v138, v[100:101], off nt
	v_lshlrev_b64 v[100:101], 12, v[2:3]
	v_lshl_add_u64 v[100:101], v[30:31], 0, v[100:101]
	global_load_dword v139, v[100:101], off nt
	v_add_u32_e32 v99, v33, v75
	v_or_b32_e32 v2, v28, v77
	v_lshlrev_b64 v[100:101], 12, v[2:3]
	v_lshl_add_u64 v[100:101], v[30:31], 0, v[100:101]
	v_or_b32_e32 v2, v28, v79
	global_load_dword v140, v[100:101], off nt
	v_lshlrev_b64 v[100:101], 12, v[2:3]
	v_lshl_add_u64 v[100:101], v[30:31], 0, v[100:101]
	global_load_dword v141, v[100:101], off nt
	v_or_b32_e32 v2, v28, v80
	v_lshlrev_b64 v[100:101], 12, v[2:3]
	v_lshl_add_u64 v[100:101], v[30:31], 0, v[100:101]
	v_or_b32_e32 v2, v28, v82
	global_load_dword v142, v[100:101], off nt
	v_lshlrev_b64 v[100:101], 12, v[2:3]
	v_lshl_add_u64 v[100:101], v[30:31], 0, v[100:101]
	global_load_dword v143, v[100:101], off nt
	v_add_u32_e32 v99, 0x400, v99
	v_or_b32_e32 v2, v28, v83
	v_lshlrev_b64 v[100:101], 12, v[2:3]
	v_lshl_add_u64 v[100:101], v[30:31], 0, v[100:101]
	v_or_b32_e32 v2, v28, v85
	global_load_dword v144, v[100:101], off nt
	v_lshlrev_b64 v[100:101], 12, v[2:3]
	v_lshl_add_u64 v[100:101], v[30:31], 0, v[100:101]
	global_load_dword v145, v[100:101], off nt
	v_add_u32_e32 v99, v33, v84
	v_or_b32_e32 v2, v28, v86
	v_lshlrev_b64 v[100:101], 12, v[2:3]
	v_lshl_add_u64 v[100:101], v[30:31], 0, v[100:101]
	v_or_b32_e32 v2, v28, v87
	global_load_dword v146, v[100:101], off nt
	v_lshlrev_b64 v[100:101], 12, v[2:3]
	v_lshl_add_u64 v[100:101], v[30:31], 0, v[100:101]
	global_load_dword v147, v[100:101], off nt
	v_or_b32_e32 v2, v28, v88
	v_lshlrev_b64 v[100:101], 12, v[2:3]
	v_lshl_add_u64 v[100:101], v[30:31], 0, v[100:101]
	v_or_b32_e32 v2, v28, v89
	global_load_dword v148, v[100:101], off nt
	v_lshlrev_b64 v[100:101], 12, v[2:3]
	v_lshl_add_u64 v[100:101], v[30:31], 0, v[100:101]
	global_load_dword v149, v[100:101], off nt
	v_add_u32_e32 v99, 0x400, v99
	v_or_b32_e32 v2, v28, v90
	v_lshlrev_b64 v[100:101], 12, v[2:3]
	v_lshl_add_u64 v[100:101], v[30:31], 0, v[100:101]
	v_or_b32_e32 v2, v28, v91
	global_load_dword v150, v[100:101], off nt
	v_lshlrev_b64 v[100:101], 12, v[2:3]
	v_lshl_add_u64 v[30:31], v[30:31], 0, v[100:101]
	global_load_dword v151, v[30:31], off nt
	v_add_u32_e32 v184, v33, v34
	s_waitcnt vmcnt(31)
	ds_write_b32 v184, v120 offset:0
	s_waitcnt vmcnt(30)
	ds_write_b32 v184, v121 offset:264
	s_waitcnt vmcnt(29)
	ds_write_b32 v184, v122 offset:528
	s_waitcnt vmcnt(28)
	ds_write_b32 v184, v123 offset:792
	s_waitcnt vmcnt(27)
	ds_write_b32 v184, v124 offset:1056
	s_waitcnt vmcnt(26)
	ds_write_b32 v184, v125 offset:1320
	s_waitcnt vmcnt(25)
	ds_write_b32 v184, v126 offset:1584
	s_waitcnt vmcnt(24)
	ds_write_b32 v184, v127 offset:1848
	s_waitcnt vmcnt(23)
	ds_write_b32 v184, v128 offset:2112
	s_waitcnt vmcnt(22)
	ds_write_b32 v184, v129 offset:2376
	s_waitcnt vmcnt(21)
	ds_write_b32 v184, v130 offset:2640
	s_waitcnt vmcnt(20)
	ds_write_b32 v184, v131 offset:2904
	s_waitcnt vmcnt(19)
	ds_write_b32 v184, v132 offset:3168
	s_waitcnt vmcnt(18)
	ds_write_b32 v184, v133 offset:3432
	s_waitcnt vmcnt(17)
	ds_write_b32 v184, v134 offset:3696
	s_waitcnt vmcnt(16)
	ds_write_b32 v184, v135 offset:3960
	s_waitcnt vmcnt(15)
	ds_write_b32 v184, v136 offset:4224
	s_waitcnt vmcnt(14)
	ds_write_b32 v184, v137 offset:4488
	s_waitcnt vmcnt(13)
	ds_write_b32 v184, v138 offset:4752
	s_waitcnt vmcnt(12)
	ds_write_b32 v184, v139 offset:5016
	s_waitcnt vmcnt(11)
	ds_write_b32 v184, v140 offset:5280
	s_waitcnt vmcnt(10)
	ds_write_b32 v184, v141 offset:5544
	s_waitcnt vmcnt(9)
	ds_write_b32 v184, v142 offset:5808
	s_waitcnt vmcnt(8)
	ds_write_b32 v184, v143 offset:6072
	s_waitcnt vmcnt(7)
	ds_write_b32 v184, v144 offset:6336
	s_waitcnt vmcnt(6)
	ds_write_b32 v184, v145 offset:6600
	s_waitcnt vmcnt(5)
	ds_write_b32 v184, v146 offset:6864
	s_waitcnt vmcnt(4)
	ds_write_b32 v184, v147 offset:7128
	s_waitcnt vmcnt(3)
	ds_write_b32 v184, v148 offset:7392
	s_waitcnt vmcnt(2)
	ds_write_b32 v184, v149 offset:7656
	s_waitcnt vmcnt(1)
	ds_write_b32 v184, v150 offset:7920
	s_waitcnt vmcnt(0)
	ds_write_b32 v184, v151 offset:8184
	s_waitcnt lgkmcnt(0)
	ds_read2_b32 v[102:103], v44 offset0:33 offset1:41
	ds_read2_b32 v[104:105], v44 offset1:8
	ds_read2_b32 v[106:107], v44 offset0:66 offset1:74
	ds_read2_b32 v[108:109], v44 offset0:99 offset1:107
	ds_read2_b32 v[110:111], v44 offset0:132 offset1:140
	ds_read2_b32 v[112:113], v44 offset0:165 offset1:173
	ds_read2_b32 v[114:115], v44 offset0:198 offset1:206
	ds_read2_b32 v[116:117], v44 offset0:231 offset1:239
	v_or_b32_e32 v2, v98, v43
	v_mov_b32_e32 v29, v3
	v_mul_u32_u24_e32 v2, 0xb00, v2
	v_lshl_add_u64 v[100:101], v[28:29], 1, v[4:5]
	v_lshlrev_b32_e32 v2, 1, v2
	v_lshl_add_u64 v[118:119], v[100:101], 0, v[2:3]
	v_or_b32_e32 v2, v98, v92
	v_mul_u32_u24_e32 v2, 0xb00, v2
	s_waitcnt lgkmcnt(6)
	v_cvt_pk_bf16_f32 v28, v104, v102
	s_waitcnt lgkmcnt(4)
	v_cvt_pk_bf16_f32 v29, v106, v108
	s_waitcnt lgkmcnt(2)
	v_cvt_pk_bf16_f32 v30, v110, v112
	s_waitcnt lgkmcnt(0)
	v_cvt_pk_bf16_f32 v31, v114, v116
	v_lshlrev_b32_e32 v2, 1, v2
	global_store_dwordx4 v[118:119], v[28:31], off
	s_nop 1
	v_cvt_pk_bf16_f32 v28, v105, v103
	v_cvt_pk_bf16_f32 v29, v107, v109
	v_cvt_pk_bf16_f32 v30, v111, v113
	v_cvt_pk_bf16_f32 v31, v115, v117
	v_lshl_add_u64 v[102:103], v[100:101], 0, v[2:3]
	global_store_dwordx4 v[102:103], v[28:31], off
	ds_read2_b32 v[102:103], v44 offset0:16 offset1:24
	ds_read2_b32 v[104:105], v44 offset0:49 offset1:57
	ds_read2_b32 v[106:107], v44 offset0:82 offset1:90
	ds_read2_b32 v[108:109], v44 offset0:115 offset1:123
	ds_read2_b32 v[110:111], v44 offset0:148 offset1:156
	ds_read2_b32 v[112:113], v44 offset0:181 offset1:189
	ds_read2_b32 v[114:115], v44 offset0:214 offset1:222
	ds_read2_b32 v[116:117], v44 offset0:247 offset1:255
	v_or_b32_e32 v2, v98, v93
	v_mul_u32_u24_e32 v2, 0xb00, v2
	v_lshlrev_b32_e32 v2, 1, v2
	v_lshl_add_u64 v[118:119], v[100:101], 0, v[2:3]
	v_or_b32_e32 v2, v98, v94
	v_mul_u32_u24_e32 v2, 0xb00, v2
	s_waitcnt lgkmcnt(6)
	v_cvt_pk_bf16_f32 v28, v102, v104
	s_waitcnt lgkmcnt(4)
	v_cvt_pk_bf16_f32 v29, v106, v108
	s_waitcnt lgkmcnt(2)
	v_cvt_pk_bf16_f32 v30, v110, v112
	s_waitcnt lgkmcnt(0)
	v_cvt_pk_bf16_f32 v31, v114, v116
	v_lshlrev_b32_e32 v2, 1, v2
	global_store_dwordx4 v[118:119], v[28:31], off
	v_lshl_add_u64 v[98:99], v[100:101], 0, v[2:3]
	s_nop 0
	v_cvt_pk_bf16_f32 v28, v103, v105
	v_cvt_pk_bf16_f32 v29, v107, v109
	v_cvt_pk_bf16_f32 v30, v111, v113
	v_cvt_pk_bf16_f32 v31, v115, v117
	global_store_dwordx4 v[98:99], v[28:31], off
	s_waitcnt lgkmcnt(0)
.LBB0_528:
	s_andn2_saveexec_b64 s[48:49], s[48:49]
	s_cbranch_execz .LBB0_530
	v_add_u16_e32 v2, 0xe680, v97
	v_mul_u32_u24_e32 v28, 0xba2f, v2
	v_lshrrev_b32_e32 v28, 23, v28
	v_mul_lo_u16_e32 v29, 0xb0, v28
	v_sub_u16_e32 v2, v2, v29
	v_bfe_i32 v29, v2, 2, 1
	v_lshlrev_b32_e32 v30, 4, v2
	v_and_b32_e32 v29, 0xb00, v29
	v_and_b32_e32 v30, 0xf80, v30
	v_add_u32_e32 v29, v29, v30
	v_lshlrev_b32_e32 v30, 5, v2
	s_movk_i32 s20, 0x60
	v_and_or_b32 v2, v30, s20, v29
	v_lshlrev_b16_e32 v31, 6, v28
	v_lshlrev_b32_e32 v2, 2, v2
	v_lshl_add_u64 v[28:29], v[18:19], 0, v[2:3]
	v_or_b32_e32 v2, v32, v31
	v_mul_u32_u24_e32 v2, 0x1600, v2
	v_lshlrev_b32_e32 v2, 2, v2
	v_lshl_add_u64 v[98:99], v[28:29], 0, v[2:3]
	v_or_b32_e32 v2, v35, v31
	v_mul_u32_u24_e32 v2, 0x1600, v2
	v_lshlrev_b32_e32 v2, 2, v2
	global_load_dword v120, v[98:99], off nt
	v_lshl_add_u64 v[98:99], v[28:29], 0, v[2:3]
	global_load_dword v121, v[98:99], off nt
	v_add_u32_e32 v101, v33, v34
	v_or_b32_e32 v2, v36, v31
	v_mul_u32_u24_e32 v2, 0x1600, v2
	v_lshlrev_b32_e32 v2, 2, v2
	v_lshl_add_u64 v[98:99], v[28:29], 0, v[2:3]
	v_or_b32_e32 v2, v38, v31
	v_mul_u32_u24_e32 v2, 0x1600, v2
	v_lshlrev_b32_e32 v2, 2, v2
	global_load_dword v122, v[98:99], off nt
	v_lshl_add_u64 v[98:99], v[28:29], 0, v[2:3]
	global_load_dword v123, v[98:99], off nt
	v_or_b32_e32 v2, v39, v31
	v_mul_u32_u24_e32 v2, 0x1600, v2
	v_lshlrev_b32_e32 v2, 2, v2
	v_lshl_add_u64 v[98:99], v[28:29], 0, v[2:3]
	v_or_b32_e32 v2, v41, v31
	v_mul_u32_u24_e32 v2, 0x1600, v2
	v_lshlrev_b32_e32 v2, 2, v2
	global_load_dword v124, v[98:99], off nt
	v_lshl_add_u64 v[98:99], v[28:29], 0, v[2:3]
	global_load_dword v125, v[98:99], off nt
	v_add_u32_e32 v98, 0x400, v101
	v_add_u32_e32 v101, v33, v57
	v_or_b32_e32 v2, v42, v31
	v_mul_u32_u24_e32 v2, 0x1600, v2
	v_lshlrev_b32_e32 v2, 2, v2
	v_lshl_add_u64 v[98:99], v[28:29], 0, v[2:3]
	v_or_b32_e32 v2, v58, v31
	v_mul_u32_u24_e32 v2, 0x1600, v2
	v_lshlrev_b32_e32 v2, 2, v2
	global_load_dword v126, v[98:99], off nt
	v_lshl_add_u64 v[98:99], v[28:29], 0, v[2:3]
	global_load_dword v127, v[98:99], off nt
	v_or_b32_e32 v2, v59, v31
	v_mul_u32_u24_e32 v2, 0x1600, v2
	v_lshlrev_b32_e32 v2, 2, v2
	v_lshl_add_u64 v[98:99], v[28:29], 0, v[2:3]
	v_or_b32_e32 v2, v61, v31
	v_mul_u32_u24_e32 v2, 0x1600, v2
	v_lshlrev_b32_e32 v2, 2, v2
	global_load_dword v128, v[98:99], off nt
	v_lshl_add_u64 v[98:99], v[28:29], 0, v[2:3]
	global_load_dword v129, v[98:99], off nt
	v_or_b32_e32 v2, v62, v31
	v_mul_u32_u24_e32 v2, 0x1600, v2
	v_lshlrev_b32_e32 v2, 2, v2
	v_lshl_add_u64 v[98:99], v[28:29], 0, v[2:3]
	v_or_b32_e32 v2, v64, v31
	v_mul_u32_u24_e32 v2, 0x1600, v2
	v_lshlrev_b32_e32 v2, 2, v2
	global_load_dword v130, v[98:99], off nt
	v_lshl_add_u64 v[98:99], v[28:29], 0, v[2:3]
	global_load_dword v131, v[98:99], off nt
	v_add_u32_e32 v98, 0x400, v101
	v_add_u32_e32 v101, v33, v66
	v_or_b32_e32 v2, v65, v31
	v_mul_u32_u24_e32 v2, 0x1600, v2
	v_lshlrev_b32_e32 v2, 2, v2
	v_lshl_add_u64 v[98:99], v[28:29], 0, v[2:3]
	v_or_b32_e32 v2, v67, v31
	v_mul_u32_u24_e32 v2, 0x1600, v2
	v_lshlrev_b32_e32 v2, 2, v2
	global_load_dword v132, v[98:99], off nt
	v_lshl_add_u64 v[98:99], v[28:29], 0, v[2:3]
	global_load_dword v133, v[98:99], off nt
	v_or_b32_e32 v2, v68, v31
	v_mul_u32_u24_e32 v2, 0x1600, v2
	v_lshlrev_b32_e32 v2, 2, v2
	v_lshl_add_u64 v[98:99], v[28:29], 0, v[2:3]
	v_or_b32_e32 v2, v70, v31
	v_mul_u32_u24_e32 v2, 0x1600, v2
	v_lshlrev_b32_e32 v2, 2, v2
	global_load_dword v134, v[98:99], off nt
	v_lshl_add_u64 v[98:99], v[28:29], 0, v[2:3]
	global_load_dword v135, v[98:99], off nt
	v_or_b32_e32 v2, v71, v31
	v_mul_u32_u24_e32 v2, 0x1600, v2
	v_lshlrev_b32_e32 v2, 2, v2
	v_lshl_add_u64 v[98:99], v[28:29], 0, v[2:3]
	v_or_b32_e32 v2, v73, v31
	v_mul_u32_u24_e32 v2, 0x1600, v2
	v_lshlrev_b32_e32 v2, 2, v2
	global_load_dword v136, v[98:99], off nt
	v_lshl_add_u64 v[98:99], v[28:29], 0, v[2:3]
	global_load_dword v137, v[98:99], off nt
	v_add_u32_e32 v98, 0x400, v101
	v_add_u32_e32 v101, v33, v75
	v_or_b32_e32 v2, v74, v31
	v_mul_u32_u24_e32 v2, 0x1600, v2
	v_lshlrev_b32_e32 v2, 2, v2
	v_lshl_add_u64 v[98:99], v[28:29], 0, v[2:3]
	v_or_b32_e32 v2, v76, v31
	v_mul_u32_u24_e32 v2, 0x1600, v2
	v_lshlrev_b32_e32 v2, 2, v2
	global_load_dword v138, v[98:99], off nt
	v_lshl_add_u64 v[98:99], v[28:29], 0, v[2:3]
	global_load_dword v139, v[98:99], off nt
	v_or_b32_e32 v2, v77, v31
	v_mul_u32_u24_e32 v2, 0x1600, v2
	v_lshlrev_b32_e32 v2, 2, v2
	v_lshl_add_u64 v[98:99], v[28:29], 0, v[2:3]
	v_or_b32_e32 v2, v79, v31
	v_mul_u32_u24_e32 v2, 0x1600, v2
	v_lshlrev_b32_e32 v2, 2, v2
	global_load_dword v140, v[98:99], off nt
	v_lshl_add_u64 v[98:99], v[28:29], 0, v[2:3]
	global_load_dword v141, v[98:99], off nt
	v_or_b32_e32 v2, v80, v31
	v_mul_u32_u24_e32 v2, 0x1600, v2
	v_lshlrev_b32_e32 v2, 2, v2
	v_lshl_add_u64 v[98:99], v[28:29], 0, v[2:3]
	v_or_b32_e32 v2, v82, v31
	v_mul_u32_u24_e32 v2, 0x1600, v2
	v_lshlrev_b32_e32 v2, 2, v2
	global_load_dword v142, v[98:99], off nt
	v_lshl_add_u64 v[98:99], v[28:29], 0, v[2:3]
	global_load_dword v143, v[98:99], off nt
	v_add_u32_e32 v98, 0x400, v101
	v_add_u32_e32 v101, v33, v84
	v_or_b32_e32 v2, v83, v31
	v_mul_u32_u24_e32 v2, 0x1600, v2
	v_lshlrev_b32_e32 v2, 2, v2
	v_lshl_add_u64 v[98:99], v[28:29], 0, v[2:3]
	v_or_b32_e32 v2, v85, v31
	v_mul_u32_u24_e32 v2, 0x1600, v2
	v_lshlrev_b32_e32 v2, 2, v2
	global_load_dword v144, v[98:99], off nt
	v_lshl_add_u64 v[98:99], v[28:29], 0, v[2:3]
	global_load_dword v145, v[98:99], off nt
	v_or_b32_e32 v2, v86, v31
	v_mul_u32_u24_e32 v2, 0x1600, v2
	v_lshlrev_b32_e32 v2, 2, v2
	v_lshl_add_u64 v[98:99], v[28:29], 0, v[2:3]
	v_or_b32_e32 v2, v87, v31
	v_mul_u32_u24_e32 v2, 0x1600, v2
	v_lshlrev_b32_e32 v2, 2, v2
	global_load_dword v146, v[98:99], off nt
	v_lshl_add_u64 v[98:99], v[28:29], 0, v[2:3]
	global_load_dword v147, v[98:99], off nt
	v_or_b32_e32 v2, v88, v31
	v_mul_u32_u24_e32 v2, 0x1600, v2
	v_lshlrev_b32_e32 v2, 2, v2
	v_lshl_add_u64 v[98:99], v[28:29], 0, v[2:3]
	v_or_b32_e32 v2, v89, v31
	v_mul_u32_u24_e32 v2, 0x1600, v2
	v_lshlrev_b32_e32 v2, 2, v2
	global_load_dword v148, v[98:99], off nt
	v_lshl_add_u64 v[98:99], v[28:29], 0, v[2:3]
	global_load_dword v149, v[98:99], off nt
	v_add_u32_e32 v101, 0x400, v101
	v_or_b32_e32 v2, v90, v31
	v_mul_u32_u24_e32 v2, 0x1600, v2
	v_lshlrev_b32_e32 v2, 2, v2
	v_lshl_add_u64 v[98:99], v[28:29], 0, v[2:3]
	v_or_b32_e32 v2, v91, v31
	v_mul_u32_u24_e32 v2, 0x1600, v2
	v_lshlrev_b32_e32 v2, 2, v2
	v_lshl_add_u64 v[28:29], v[28:29], 0, v[2:3]
	global_load_dword v150, v[98:99], off nt
	s_nop 0
	global_load_dword v151, v[28:29], off nt
	v_add_u32_e32 v184, v33, v34
	s_waitcnt vmcnt(31)
	ds_write_b32 v184, v120 offset:0
	s_waitcnt vmcnt(30)
	ds_write_b32 v184, v121 offset:264
	s_waitcnt vmcnt(29)
	ds_write_b32 v184, v122 offset:528
	s_waitcnt vmcnt(28)
	ds_write_b32 v184, v123 offset:792
	s_waitcnt vmcnt(27)
	ds_write_b32 v184, v124 offset:1056
	s_waitcnt vmcnt(26)
	ds_write_b32 v184, v125 offset:1320
	s_waitcnt vmcnt(25)
	ds_write_b32 v184, v126 offset:1584
	s_waitcnt vmcnt(24)
	ds_write_b32 v184, v127 offset:1848
	s_waitcnt vmcnt(23)
	ds_write_b32 v184, v128 offset:2112
	s_waitcnt vmcnt(22)
	ds_write_b32 v184, v129 offset:2376
	s_waitcnt vmcnt(21)
	ds_write_b32 v184, v130 offset:2640
	s_waitcnt vmcnt(20)
	ds_write_b32 v184, v131 offset:2904
	s_waitcnt vmcnt(19)
	ds_write_b32 v184, v132 offset:3168
	s_waitcnt vmcnt(18)
	ds_write_b32 v184, v133 offset:3432
	s_waitcnt vmcnt(17)
	ds_write_b32 v184, v134 offset:3696
	s_waitcnt vmcnt(16)
	ds_write_b32 v184, v135 offset:3960
	s_waitcnt vmcnt(15)
	ds_write_b32 v184, v136 offset:4224
	s_waitcnt vmcnt(14)
	ds_write_b32 v184, v137 offset:4488
	s_waitcnt vmcnt(13)
	ds_write_b32 v184, v138 offset:4752
	s_waitcnt vmcnt(12)
	ds_write_b32 v184, v139 offset:5016
	s_waitcnt vmcnt(11)
	ds_write_b32 v184, v140 offset:5280
	s_waitcnt vmcnt(10)
	ds_write_b32 v184, v141 offset:5544
	s_waitcnt vmcnt(9)
	ds_write_b32 v184, v142 offset:5808
	s_waitcnt vmcnt(8)
	ds_write_b32 v184, v143 offset:6072
	s_waitcnt vmcnt(7)
	ds_write_b32 v184, v144 offset:6336
	s_waitcnt vmcnt(6)
	ds_write_b32 v184, v145 offset:6600
	s_waitcnt vmcnt(5)
	ds_write_b32 v184, v146 offset:6864
	s_waitcnt vmcnt(4)
	ds_write_b32 v184, v147 offset:7128
	s_waitcnt vmcnt(3)
	ds_write_b32 v184, v148 offset:7392
	s_waitcnt vmcnt(2)
	ds_write_b32 v184, v149 offset:7656
	s_waitcnt vmcnt(1)
	ds_write_b32 v184, v150 offset:7920
	s_waitcnt vmcnt(0)
	ds_write_b32 v184, v151 offset:8184
	s_waitcnt lgkmcnt(0)
	ds_read2_b32 v[102:103], v44 offset0:33 offset1:41
	ds_read2_b32 v[104:105], v44 offset1:8
	ds_read2_b32 v[106:107], v44 offset0:66 offset1:74
	ds_read2_b32 v[108:109], v44 offset0:99 offset1:107
	ds_read2_b32 v[110:111], v44 offset0:132 offset1:140
	ds_read2_b32 v[112:113], v44 offset0:165 offset1:173
	ds_read2_b32 v[114:115], v44 offset0:198 offset1:206
	ds_read2_b32 v[116:117], v44 offset0:231 offset1:239
	v_lshlrev_b32_e32 v2, 1, v31
	v_lshl_add_u64 v[28:29], v[6:7], 0, v[2:3]
	v_or_b32_e32 v2, v30, v43
	v_lshlrev_b32_e32 v2, 11, v2
	v_lshl_add_u64 v[118:119], v[28:29], 0, v[2:3]
	v_or_b32_e32 v2, v30, v92
	s_waitcnt lgkmcnt(6)
	v_cvt_pk_bf16_f32 v98, v104, v102
	s_waitcnt lgkmcnt(4)
	v_cvt_pk_bf16_f32 v99, v106, v108
	s_waitcnt lgkmcnt(2)
	v_cvt_pk_bf16_f32 v100, v110, v112
	s_waitcnt lgkmcnt(0)
	v_cvt_pk_bf16_f32 v101, v114, v116
	v_lshlrev_b32_e32 v2, 11, v2
	global_store_dwordx4 v[118:119], v[98:101], off
	s_nop 1
	v_cvt_pk_bf16_f32 v98, v105, v103
	v_cvt_pk_bf16_f32 v99, v107, v109
	v_cvt_pk_bf16_f32 v100, v111, v113
	v_cvt_pk_bf16_f32 v101, v115, v117
	v_lshl_add_u64 v[102:103], v[28:29], 0, v[2:3]
	global_store_dwordx4 v[102:103], v[98:101], off
	ds_read2_b32 v[102:103], v44 offset0:49 offset1:57
	ds_read2_b32 v[104:105], v44 offset0:16 offset1:24
	ds_read2_b32 v[106:107], v44 offset0:82 offset1:90
	ds_read2_b32 v[108:109], v44 offset0:115 offset1:123
	ds_read2_b32 v[110:111], v44 offset0:148 offset1:156
	ds_read2_b32 v[112:113], v44 offset0:181 offset1:189
	ds_read2_b32 v[114:115], v44 offset0:214 offset1:222
	ds_read2_b32 v[116:117], v44 offset0:247 offset1:255
	v_or_b32_e32 v2, v30, v93
	v_lshlrev_b32_e32 v2, 11, v2
	v_lshl_add_u64 v[118:119], v[28:29], 0, v[2:3]
	v_or_b32_e32 v2, v30, v94
	s_waitcnt lgkmcnt(6)
	v_cvt_pk_bf16_f32 v98, v104, v102
	s_waitcnt lgkmcnt(4)
	v_cvt_pk_bf16_f32 v99, v106, v108
	s_waitcnt lgkmcnt(2)
	v_cvt_pk_bf16_f32 v100, v110, v112
	s_waitcnt lgkmcnt(0)
	v_cvt_pk_bf16_f32 v101, v114, v116
	v_lshlrev_b32_e32 v2, 11, v2
	global_store_dwordx4 v[118:119], v[98:101], off
	v_lshl_add_u64 v[28:29], v[28:29], 0, v[2:3]
	s_nop 0
	v_cvt_pk_bf16_f32 v98, v105, v103
	v_cvt_pk_bf16_f32 v99, v107, v109
	v_cvt_pk_bf16_f32 v100, v111, v113
	v_cvt_pk_bf16_f32 v101, v115, v117
	global_store_dwordx4 v[28:29], v[98:101], off
	s_waitcnt lgkmcnt(0)

.LBB0_531:
	s_andn2_saveexec_b64 s[46:47], s[46:47]
	s_cbranch_execz .LBB0_533
	v_and_b32_e32 v2, 0x3fc0, v96
	v_and_b32_e32 v98, 0x3e0, v95
	v_add_u32_e32 v28, 0xffffd100, v2
	v_lshlrev_b32_e32 v2, 2, v98
	v_lshl_add_u64 v[30:31], v[20:21], 0, v[2:3]
	v_or_b32_e32 v2, v28, v32
	v_lshlrev_b64 v[100:101], 12, v[2:3]
	v_lshl_add_u64 v[100:101], v[30:31], 0, v[100:101]
	v_or_b32_e32 v2, v28, v35
	global_load_dword v120, v[100:101], off nt
	v_lshlrev_b64 v[100:101], 12, v[2:3]
	v_lshl_add_u64 v[100:101], v[30:31], 0, v[100:101]
	global_load_dword v121, v[100:101], off nt
	v_add_u32_e32 v99, v33, v34
	v_or_b32_e32 v2, v28, v36
	v_lshlrev_b64 v[100:101], 12, v[2:3]
	v_lshl_add_u64 v[100:101], v[30:31], 0, v[100:101]
	v_or_b32_e32 v2, v28, v38
	global_load_dword v122, v[100:101], off nt
	v_lshlrev_b64 v[100:101], 12, v[2:3]
	v_lshl_add_u64 v[100:101], v[30:31], 0, v[100:101]
	global_load_dword v123, v[100:101], off nt
	v_or_b32_e32 v2, v28, v39
	v_lshlrev_b64 v[100:101], 12, v[2:3]
	v_lshl_add_u64 v[100:101], v[30:31], 0, v[100:101]
	v_or_b32_e32 v2, v28, v41
	global_load_dword v124, v[100:101], off nt
	v_lshlrev_b64 v[100:101], 12, v[2:3]
	v_lshl_add_u64 v[100:101], v[30:31], 0, v[100:101]
	global_load_dword v125, v[100:101], off nt
	v_add_u32_e32 v99, 0x400, v99
	v_or_b32_e32 v2, v28, v42
	v_lshlrev_b64 v[100:101], 12, v[2:3]
	v_lshl_add_u64 v[100:101], v[30:31], 0, v[100:101]
	v_or_b32_e32 v2, v28, v58
	global_load_dword v126, v[100:101], off nt
	v_lshlrev_b64 v[100:101], 12, v[2:3]
	v_lshl_add_u64 v[100:101], v[30:31], 0, v[100:101]
	global_load_dword v127, v[100:101], off nt
	v_add_u32_e32 v99, v33, v57
	v_or_b32_e32 v2, v28, v59
	v_lshlrev_b64 v[100:101], 12, v[2:3]
	v_lshl_add_u64 v[100:101], v[30:31], 0, v[100:101]
	v_or_b32_e32 v2, v28, v61
	global_load_dword v128, v[100:101], off nt
	v_lshlrev_b64 v[100:101], 12, v[2:3]
	v_lshl_add_u64 v[100:101], v[30:31], 0, v[100:101]
	global_load_dword v129, v[100:101], off nt
	v_or_b32_e32 v2, v28, v62
	v_lshlrev_b64 v[100:101], 12, v[2:3]
	v_lshl_add_u64 v[100:101], v[30:31], 0, v[100:101]
	v_or_b32_e32 v2, v28, v64
	global_load_dword v130, v[100:101], off nt
	v_lshlrev_b64 v[100:101], 12, v[2:3]
	v_lshl_add_u64 v[100:101], v[30:31], 0, v[100:101]
	global_load_dword v131, v[100:101], off nt
	v_add_u32_e32 v99, 0x400, v99
	v_or_b32_e32 v2, v28, v65
	v_lshlrev_b64 v[100:101], 12, v[2:3]
	v_lshl_add_u64 v[100:101], v[30:31], 0, v[100:101]
	v_or_b32_e32 v2, v28, v67
	global_load_dword v132, v[100:101], off nt
	v_lshlrev_b64 v[100:101], 12, v[2:3]
	v_lshl_add_u64 v[100:101], v[30:31], 0, v[100:101]
	global_load_dword v133, v[100:101], off nt
	v_add_u32_e32 v99, v33, v66
	v_or_b32_e32 v2, v28, v68
	v_lshlrev_b64 v[100:101], 12, v[2:3]
	v_lshl_add_u64 v[100:101], v[30:31], 0, v[100:101]
	v_or_b32_e32 v2, v28, v70
	global_load_dword v134, v[100:101], off nt
	v_lshlrev_b64 v[100:101], 12, v[2:3]
	v_lshl_add_u64 v[100:101], v[30:31], 0, v[100:101]
	global_load_dword v135, v[100:101], off nt
	v_or_b32_e32 v2, v28, v71
	v_lshlrev_b64 v[100:101], 12, v[2:3]
	v_lshl_add_u64 v[100:101], v[30:31], 0, v[100:101]
	v_or_b32_e32 v2, v28, v73
	global_load_dword v136, v[100:101], off nt
	v_lshlrev_b64 v[100:101], 12, v[2:3]
	v_lshl_add_u64 v[100:101], v[30:31], 0, v[100:101]
	global_load_dword v137, v[100:101], off nt
	v_add_u32_e32 v99, 0x400, v99
	v_or_b32_e32 v2, v28, v74
	v_lshlrev_b64 v[100:101], 12, v[2:3]
	v_lshl_add_u64 v[100:101], v[30:31], 0, v[100:101]
	v_or_b32_e32 v2, v28, v76
	global_load_dword v138, v[100:101], off nt
	v_lshlrev_b64 v[100:101], 12, v[2:3]
	v_lshl_add_u64 v[100:101], v[30:31], 0, v[100:101]
	global_load_dword v139, v[100:101], off nt
	v_add_u32_e32 v99, v33, v75
	v_or_b32_e32 v2, v28, v77
	v_lshlrev_b64 v[100:101], 12, v[2:3]
	v_lshl_add_u64 v[100:101], v[30:31], 0, v[100:101]
	v_or_b32_e32 v2, v28, v79
	global_load_dword v140, v[100:101], off nt
	v_lshlrev_b64 v[100:101], 12, v[2:3]
	v_lshl_add_u64 v[100:101], v[30:31], 0, v[100:101]
	global_load_dword v141, v[100:101], off nt
	v_or_b32_e32 v2, v28, v80
	v_lshlrev_b64 v[100:101], 12, v[2:3]
	v_lshl_add_u64 v[100:101], v[30:31], 0, v[100:101]
	v_or_b32_e32 v2, v28, v82
	global_load_dword v142, v[100:101], off nt
	v_lshlrev_b64 v[100:101], 12, v[2:3]
	v_lshl_add_u64 v[100:101], v[30:31], 0, v[100:101]
	global_load_dword v143, v[100:101], off nt
	v_add_u32_e32 v99, 0x400, v99
	v_or_b32_e32 v2, v28, v83
	v_lshlrev_b64 v[100:101], 12, v[2:3]
	v_lshl_add_u64 v[100:101], v[30:31], 0, v[100:101]
	v_or_b32_e32 v2, v28, v85
	global_load_dword v144, v[100:101], off nt
	v_lshlrev_b64 v[100:101], 12, v[2:3]
	v_lshl_add_u64 v[100:101], v[30:31], 0, v[100:101]
	global_load_dword v145, v[100:101], off nt
	v_add_u32_e32 v99, v33, v84
	v_or_b32_e32 v2, v28, v86
	v_lshlrev_b64 v[100:101], 12, v[2:3]
	v_lshl_add_u64 v[100:101], v[30:31], 0, v[100:101]
	v_or_b32_e32 v2, v28, v87
	global_load_dword v146, v[100:101], off nt
	v_lshlrev_b64 v[100:101], 12, v[2:3]
	v_lshl_add_u64 v[100:101], v[30:31], 0, v[100:101]
	global_load_dword v147, v[100:101], off nt
	v_or_b32_e32 v2, v28, v88
	v_lshlrev_b64 v[100:101], 12, v[2:3]
	v_lshl_add_u64 v[100:101], v[30:31], 0, v[100:101]
	v_or_b32_e32 v2, v28, v89
	global_load_dword v148, v[100:101], off nt
	v_lshlrev_b64 v[100:101], 12, v[2:3]
	v_lshl_add_u64 v[100:101], v[30:31], 0, v[100:101]
	global_load_dword v149, v[100:101], off nt
	v_add_u32_e32 v99, 0x400, v99
	v_or_b32_e32 v2, v28, v90
	v_lshlrev_b64 v[100:101], 12, v[2:3]
	v_lshl_add_u64 v[100:101], v[30:31], 0, v[100:101]
	v_or_b32_e32 v2, v28, v91
	global_load_dword v150, v[100:101], off nt
	v_lshlrev_b64 v[100:101], 12, v[2:3]
	v_lshl_add_u64 v[30:31], v[30:31], 0, v[100:101]
	global_load_dword v151, v[30:31], off nt
	v_add_u32_e32 v184, v33, v34
	s_waitcnt vmcnt(31)
	ds_write_b32 v184, v120 offset:0
	s_waitcnt vmcnt(30)
	ds_write_b32 v184, v121 offset:264
	s_waitcnt vmcnt(29)
	ds_write_b32 v184, v122 offset:528
	s_waitcnt vmcnt(28)
	ds_write_b32 v184, v123 offset:792
	s_waitcnt vmcnt(27)
	ds_write_b32 v184, v124 offset:1056
	s_waitcnt vmcnt(26)
	ds_write_b32 v184, v125 offset:1320
	s_waitcnt vmcnt(25)
	ds_write_b32 v184, v126 offset:1584
	s_waitcnt vmcnt(24)
	ds_write_b32 v184, v127 offset:1848
	s_waitcnt vmcnt(23)
	ds_write_b32 v184, v128 offset:2112
	s_waitcnt vmcnt(22)
	ds_write_b32 v184, v129 offset:2376
	s_waitcnt vmcnt(21)
	ds_write_b32 v184, v130 offset:2640
	s_waitcnt vmcnt(20)
	ds_write_b32 v184, v131 offset:2904
	s_waitcnt vmcnt(19)
	ds_write_b32 v184, v132 offset:3168
	s_waitcnt vmcnt(18)
	ds_write_b32 v184, v133 offset:3432
	s_waitcnt vmcnt(17)
	ds_write_b32 v184, v134 offset:3696
	s_waitcnt vmcnt(16)
	ds_write_b32 v184, v135 offset:3960
	s_waitcnt vmcnt(15)
	ds_write_b32 v184, v136 offset:4224
	s_waitcnt vmcnt(14)
	ds_write_b32 v184, v137 offset:4488
	s_waitcnt vmcnt(13)
	ds_write_b32 v184, v138 offset:4752
	s_waitcnt vmcnt(12)
	ds_write_b32 v184, v139 offset:5016
	s_waitcnt vmcnt(11)
	ds_write_b32 v184, v140 offset:5280
	s_waitcnt vmcnt(10)
	ds_write_b32 v184, v141 offset:5544
	s_waitcnt vmcnt(9)
	ds_write_b32 v184, v142 offset:5808
	s_waitcnt vmcnt(8)
	ds_write_b32 v184, v143 offset:6072
	s_waitcnt vmcnt(7)
	ds_write_b32 v184, v144 offset:6336
	s_waitcnt vmcnt(6)
	ds_write_b32 v184, v145 offset:6600
	s_waitcnt vmcnt(5)
	ds_write_b32 v184, v146 offset:6864
	s_waitcnt vmcnt(4)
	ds_write_b32 v184, v147 offset:7128
	s_waitcnt vmcnt(3)
	ds_write_b32 v184, v148 offset:7392
	s_waitcnt vmcnt(2)
	ds_write_b32 v184, v149 offset:7656
	s_waitcnt vmcnt(1)
	ds_write_b32 v184, v150 offset:7920
	s_waitcnt vmcnt(0)
	ds_write_b32 v184, v151 offset:8184
	s_waitcnt lgkmcnt(0)
	ds_read2_b32 v[102:103], v44 offset0:33 offset1:41
	ds_read2_b32 v[104:105], v44 offset1:8
	ds_read2_b32 v[106:107], v44 offset0:66 offset1:74
	ds_read2_b32 v[108:109], v44 offset0:99 offset1:107
	ds_read2_b32 v[110:111], v44 offset0:132 offset1:140
	ds_read2_b32 v[112:113], v44 offset0:165 offset1:173
	ds_read2_b32 v[114:115], v44 offset0:198 offset1:206
	ds_read2_b32 v[116:117], v44 offset0:231 offset1:239
	v_mov_b32_e32 v29, v3
	v_or_b32_e32 v2, v98, v43
	v_lshl_add_u64 v[100:101], v[28:29], 1, v[8:9]
	v_lshlrev_b32_e32 v2, 11, v2
	v_lshl_add_u64 v[118:119], v[100:101], 0, v[2:3]
	v_or_b32_e32 v2, v98, v92
	s_waitcnt lgkmcnt(6)
	v_cvt_pk_bf16_f32 v28, v104, v102
	s_waitcnt lgkmcnt(4)
	v_cvt_pk_bf16_f32 v29, v106, v108
	s_waitcnt lgkmcnt(2)
	v_cvt_pk_bf16_f32 v30, v110, v112
	s_waitcnt lgkmcnt(0)
	v_cvt_pk_bf16_f32 v31, v114, v116
	v_lshlrev_b32_e32 v2, 11, v2
	global_store_dwordx4 v[118:119], v[28:31], off
	s_nop 1
	v_cvt_pk_bf16_f32 v28, v105, v103
	v_cvt_pk_bf16_f32 v29, v107, v109
	v_cvt_pk_bf16_f32 v30, v111, v113
	v_cvt_pk_bf16_f32 v31, v115, v117
	v_lshl_add_u64 v[102:103], v[100:101], 0, v[2:3]
	global_store_dwordx4 v[102:103], v[28:31], off
	ds_read2_b32 v[102:103], v44 offset0:49 offset1:57
	ds_read2_b32 v[104:105], v44 offset0:16 offset1:24
	ds_read2_b32 v[106:107], v44 offset0:82 offset1:90
	ds_read2_b32 v[108:109], v44 offset0:115 offset1:123
	ds_read2_b32 v[110:111], v44 offset0:148 offset1:156
	ds_read2_b32 v[112:113], v44 offset0:181 offset1:189
	ds_read2_b32 v[114:115], v44 offset0:214 offset1:222
	ds_read2_b32 v[116:117], v44 offset0:247 offset1:255
	v_or_b32_e32 v2, v98, v93
	v_lshlrev_b32_e32 v2, 11, v2
	v_lshl_add_u64 v[118:119], v[100:101], 0, v[2:3]
	v_or_b32_e32 v2, v98, v94
	s_waitcnt lgkmcnt(6)
	v_cvt_pk_bf16_f32 v28, v104, v102
	s_waitcnt lgkmcnt(4)
	v_cvt_pk_bf16_f32 v29, v106, v108
	s_waitcnt lgkmcnt(2)
	v_cvt_pk_bf16_f32 v30, v110, v112
	s_waitcnt lgkmcnt(0)
	v_cvt_pk_bf16_f32 v31, v114, v116
	v_lshlrev_b32_e32 v2, 11, v2
	global_store_dwordx4 v[118:119], v[28:31], off
	v_lshl_add_u64 v[98:99], v[100:101], 0, v[2:3]
	s_nop 0
	v_cvt_pk_bf16_f32 v28, v105, v103
	v_cvt_pk_bf16_f32 v29, v107, v109
	v_cvt_pk_bf16_f32 v30, v111, v113
	v_cvt_pk_bf16_f32 v31, v115, v117
	global_store_dwordx4 v[98:99], v[28:31], off
	s_waitcnt lgkmcnt(0)

.LBB0_534:
	s_andn2_saveexec_b64 s[44:45], s[44:45]
	s_cbranch_execz .LBB0_536
	v_and_b32_e32 v2, 0x3fc0, v96
	v_and_b32_e32 v98, 0x3e0, v95
	v_add_u32_e32 v28, 0xffffd500, v2
	v_lshlrev_b32_e32 v2, 2, v98
	v_lshl_add_u64 v[30:31], v[22:23], 0, v[2:3]
	v_or_b32_e32 v2, v28, v32
	v_lshlrev_b64 v[100:101], 12, v[2:3]
	v_lshl_add_u64 v[100:101], v[30:31], 0, v[100:101]
	v_or_b32_e32 v2, v28, v35
	global_load_dword v120, v[100:101], off nt
	v_lshlrev_b64 v[100:101], 12, v[2:3]
	v_lshl_add_u64 v[100:101], v[30:31], 0, v[100:101]
	global_load_dword v121, v[100:101], off nt
	v_add_u32_e32 v99, v33, v34
	v_or_b32_e32 v2, v28, v36
	v_lshlrev_b64 v[100:101], 12, v[2:3]
	v_lshl_add_u64 v[100:101], v[30:31], 0, v[100:101]
	v_or_b32_e32 v2, v28, v38
	global_load_dword v122, v[100:101], off nt
	v_lshlrev_b64 v[100:101], 12, v[2:3]
	v_lshl_add_u64 v[100:101], v[30:31], 0, v[100:101]
	global_load_dword v123, v[100:101], off nt
	v_or_b32_e32 v2, v28, v39
	v_lshlrev_b64 v[100:101], 12, v[2:3]
	v_lshl_add_u64 v[100:101], v[30:31], 0, v[100:101]
	v_or_b32_e32 v2, v28, v41
	global_load_dword v124, v[100:101], off nt
	v_lshlrev_b64 v[100:101], 12, v[2:3]
	v_lshl_add_u64 v[100:101], v[30:31], 0, v[100:101]
	global_load_dword v125, v[100:101], off nt
	v_add_u32_e32 v99, 0x400, v99
	v_or_b32_e32 v2, v28, v42
	v_lshlrev_b64 v[100:101], 12, v[2:3]
	v_lshl_add_u64 v[100:101], v[30:31], 0, v[100:101]
	v_or_b32_e32 v2, v28, v58
	global_load_dword v126, v[100:101], off nt
	v_lshlrev_b64 v[100:101], 12, v[2:3]
	v_lshl_add_u64 v[100:101], v[30:31], 0, v[100:101]
	global_load_dword v127, v[100:101], off nt
	v_add_u32_e32 v99, v33, v57
	v_or_b32_e32 v2, v28, v59
	v_lshlrev_b64 v[100:101], 12, v[2:3]
	v_lshl_add_u64 v[100:101], v[30:31], 0, v[100:101]
	v_or_b32_e32 v2, v28, v61
	global_load_dword v128, v[100:101], off nt
	v_lshlrev_b64 v[100:101], 12, v[2:3]
	v_lshl_add_u64 v[100:101], v[30:31], 0, v[100:101]
	global_load_dword v129, v[100:101], off nt
	v_or_b32_e32 v2, v28, v62
	v_lshlrev_b64 v[100:101], 12, v[2:3]
	v_lshl_add_u64 v[100:101], v[30:31], 0, v[100:101]
	v_or_b32_e32 v2, v28, v64
	global_load_dword v130, v[100:101], off nt
	v_lshlrev_b64 v[100:101], 12, v[2:3]
	v_lshl_add_u64 v[100:101], v[30:31], 0, v[100:101]
	global_load_dword v131, v[100:101], off nt
	v_add_u32_e32 v99, 0x400, v99
	v_or_b32_e32 v2, v28, v65
	v_lshlrev_b64 v[100:101], 12, v[2:3]
	v_lshl_add_u64 v[100:101], v[30:31], 0, v[100:101]
	v_or_b32_e32 v2, v28, v67
	global_load_dword v132, v[100:101], off nt
	v_lshlrev_b64 v[100:101], 12, v[2:3]
	v_lshl_add_u64 v[100:101], v[30:31], 0, v[100:101]
	global_load_dword v133, v[100:101], off nt
	v_add_u32_e32 v99, v33, v66
	v_or_b32_e32 v2, v28, v68
	v_lshlrev_b64 v[100:101], 12, v[2:3]
	v_lshl_add_u64 v[100:101], v[30:31], 0, v[100:101]
	v_or_b32_e32 v2, v28, v70
	global_load_dword v134, v[100:101], off nt
	v_lshlrev_b64 v[100:101], 12, v[2:3]
	v_lshl_add_u64 v[100:101], v[30:31], 0, v[100:101]
	global_load_dword v135, v[100:101], off nt
	v_or_b32_e32 v2, v28, v71
	v_lshlrev_b64 v[100:101], 12, v[2:3]
	v_lshl_add_u64 v[100:101], v[30:31], 0, v[100:101]
	v_or_b32_e32 v2, v28, v73
	global_load_dword v136, v[100:101], off nt
	v_lshlrev_b64 v[100:101], 12, v[2:3]
	v_lshl_add_u64 v[100:101], v[30:31], 0, v[100:101]
	global_load_dword v137, v[100:101], off nt
	v_add_u32_e32 v99, 0x400, v99
	v_or_b32_e32 v2, v28, v74
	v_lshlrev_b64 v[100:101], 12, v[2:3]
	v_lshl_add_u64 v[100:101], v[30:31], 0, v[100:101]
	v_or_b32_e32 v2, v28, v76
	global_load_dword v138, v[100:101], off nt
	v_lshlrev_b64 v[100:101], 12, v[2:3]
	v_lshl_add_u64 v[100:101], v[30:31], 0, v[100:101]
	global_load_dword v139, v[100:101], off nt
	v_add_u32_e32 v99, v33, v75
	v_or_b32_e32 v2, v28, v77
	v_lshlrev_b64 v[100:101], 12, v[2:3]
	v_lshl_add_u64 v[100:101], v[30:31], 0, v[100:101]
	v_or_b32_e32 v2, v28, v79
	global_load_dword v140, v[100:101], off nt
	v_lshlrev_b64 v[100:101], 12, v[2:3]
	v_lshl_add_u64 v[100:101], v[30:31], 0, v[100:101]
	global_load_dword v141, v[100:101], off nt
	v_or_b32_e32 v2, v28, v80
	v_lshlrev_b64 v[100:101], 12, v[2:3]
	v_lshl_add_u64 v[100:101], v[30:31], 0, v[100:101]
	v_or_b32_e32 v2, v28, v82
	global_load_dword v142, v[100:101], off nt
	v_lshlrev_b64 v[100:101], 12, v[2:3]
	v_lshl_add_u64 v[100:101], v[30:31], 0, v[100:101]
	global_load_dword v143, v[100:101], off nt
	v_add_u32_e32 v99, 0x400, v99
	v_or_b32_e32 v2, v28, v83
	v_lshlrev_b64 v[100:101], 12, v[2:3]
	v_lshl_add_u64 v[100:101], v[30:31], 0, v[100:101]
	v_or_b32_e32 v2, v28, v85
	global_load_dword v144, v[100:101], off nt
	v_lshlrev_b64 v[100:101], 12, v[2:3]
	v_lshl_add_u64 v[100:101], v[30:31], 0, v[100:101]
	global_load_dword v145, v[100:101], off nt
	v_add_u32_e32 v99, v33, v84
	v_or_b32_e32 v2, v28, v86
	v_lshlrev_b64 v[100:101], 12, v[2:3]
	v_lshl_add_u64 v[100:101], v[30:31], 0, v[100:101]
	v_or_b32_e32 v2, v28, v87
	global_load_dword v146, v[100:101], off nt
	v_lshlrev_b64 v[100:101], 12, v[2:3]
	v_lshl_add_u64 v[100:101], v[30:31], 0, v[100:101]
	global_load_dword v147, v[100:101], off nt
	v_or_b32_e32 v2, v28, v88
	v_lshlrev_b64 v[100:101], 12, v[2:3]
	v_lshl_add_u64 v[100:101], v[30:31], 0, v[100:101]
	v_or_b32_e32 v2, v28, v89
	global_load_dword v148, v[100:101], off nt
	v_lshlrev_b64 v[100:101], 12, v[2:3]
	v_lshl_add_u64 v[100:101], v[30:31], 0, v[100:101]
	global_load_dword v149, v[100:101], off nt
	v_add_u32_e32 v99, 0x400, v99
	v_or_b32_e32 v2, v28, v90
	v_lshlrev_b64 v[100:101], 12, v[2:3]
	v_lshl_add_u64 v[100:101], v[30:31], 0, v[100:101]
	v_or_b32_e32 v2, v28, v91
	global_load_dword v150, v[100:101], off nt
	v_lshlrev_b64 v[100:101], 12, v[2:3]
	v_lshl_add_u64 v[30:31], v[30:31], 0, v[100:101]
	global_load_dword v151, v[30:31], off nt
	v_add_u32_e32 v184, v33, v34
	s_waitcnt vmcnt(31)
	ds_write_b32 v184, v120 offset:0
	s_waitcnt vmcnt(30)
	ds_write_b32 v184, v121 offset:264
	s_waitcnt vmcnt(29)
	ds_write_b32 v184, v122 offset:528
	s_waitcnt vmcnt(28)
	ds_write_b32 v184, v123 offset:792
	s_waitcnt vmcnt(27)
	ds_write_b32 v184, v124 offset:1056
	s_waitcnt vmcnt(26)
	ds_write_b32 v184, v125 offset:1320
	s_waitcnt vmcnt(25)
	ds_write_b32 v184, v126 offset:1584
	s_waitcnt vmcnt(24)
	ds_write_b32 v184, v127 offset:1848
	s_waitcnt vmcnt(23)
	ds_write_b32 v184, v128 offset:2112
	s_waitcnt vmcnt(22)
	ds_write_b32 v184, v129 offset:2376
	s_waitcnt vmcnt(21)
	ds_write_b32 v184, v130 offset:2640
	s_waitcnt vmcnt(20)
	ds_write_b32 v184, v131 offset:2904
	s_waitcnt vmcnt(19)
	ds_write_b32 v184, v132 offset:3168
	s_waitcnt vmcnt(18)
	ds_write_b32 v184, v133 offset:3432
	s_waitcnt vmcnt(17)
	ds_write_b32 v184, v134 offset:3696
	s_waitcnt vmcnt(16)
	ds_write_b32 v184, v135 offset:3960
	s_waitcnt vmcnt(15)
	ds_write_b32 v184, v136 offset:4224
	s_waitcnt vmcnt(14)
	ds_write_b32 v184, v137 offset:4488
	s_waitcnt vmcnt(13)
	ds_write_b32 v184, v138 offset:4752
	s_waitcnt vmcnt(12)
	ds_write_b32 v184, v139 offset:5016
	s_waitcnt vmcnt(11)
	ds_write_b32 v184, v140 offset:5280
	s_waitcnt vmcnt(10)
	ds_write_b32 v184, v141 offset:5544
	s_waitcnt vmcnt(9)
	ds_write_b32 v184, v142 offset:5808
	s_waitcnt vmcnt(8)
	ds_write_b32 v184, v143 offset:6072
	s_waitcnt vmcnt(7)
	ds_write_b32 v184, v144 offset:6336
	s_waitcnt vmcnt(6)
	ds_write_b32 v184, v145 offset:6600
	s_waitcnt vmcnt(5)
	ds_write_b32 v184, v146 offset:6864
	s_waitcnt vmcnt(4)
	ds_write_b32 v184, v147 offset:7128
	s_waitcnt vmcnt(3)
	ds_write_b32 v184, v148 offset:7392
	s_waitcnt vmcnt(2)
	ds_write_b32 v184, v149 offset:7656
	s_waitcnt vmcnt(1)
	ds_write_b32 v184, v150 offset:7920
	s_waitcnt vmcnt(0)
	ds_write_b32 v184, v151 offset:8184
	s_waitcnt lgkmcnt(0)
	ds_read2_b32 v[102:103], v44 offset0:33 offset1:41
	ds_read2_b32 v[104:105], v44 offset1:8
	ds_read2_b32 v[106:107], v44 offset0:66 offset1:74
	ds_read2_b32 v[108:109], v44 offset0:99 offset1:107
	ds_read2_b32 v[110:111], v44 offset0:132 offset1:140
	ds_read2_b32 v[112:113], v44 offset0:165 offset1:173
	ds_read2_b32 v[114:115], v44 offset0:198 offset1:206
	ds_read2_b32 v[116:117], v44 offset0:231 offset1:239
	v_or_b32_e32 v2, v98, v43
	v_mov_b32_e32 v29, v3
	v_mul_u32_u24_e32 v2, 0xc00, v2
	v_lshl_add_u64 v[100:101], v[28:29], 1, v[10:11]
	v_lshlrev_b32_e32 v2, 1, v2
	v_lshl_add_u64 v[118:119], v[100:101], 0, v[2:3]
	v_or_b32_e32 v2, v98, v92
	v_mul_u32_u24_e32 v2, 0xc00, v2
	s_waitcnt lgkmcnt(6)
	v_cvt_pk_bf16_f32 v28, v104, v102
	s_waitcnt lgkmcnt(4)
	v_cvt_pk_bf16_f32 v29, v106, v108
	s_waitcnt lgkmcnt(2)
	v_cvt_pk_bf16_f32 v30, v110, v112
	s_waitcnt lgkmcnt(0)
	v_cvt_pk_bf16_f32 v31, v114, v116
	v_lshlrev_b32_e32 v2, 1, v2
	global_store_dwordx4 v[118:119], v[28:31], off
	s_nop 1
	v_cvt_pk_bf16_f32 v28, v105, v103
	v_cvt_pk_bf16_f32 v29, v107, v109
	v_cvt_pk_bf16_f32 v30, v111, v113
	v_cvt_pk_bf16_f32 v31, v115, v117
	v_lshl_add_u64 v[102:103], v[100:101], 0, v[2:3]
	global_store_dwordx4 v[102:103], v[28:31], off
	ds_read2_b32 v[102:103], v44 offset0:16 offset1:24
	ds_read2_b32 v[104:105], v44 offset0:49 offset1:57
	ds_read2_b32 v[106:107], v44 offset0:82 offset1:90
	ds_read2_b32 v[108:109], v44 offset0:115 offset1:123
	ds_read2_b32 v[110:111], v44 offset0:148 offset1:156
	ds_read2_b32 v[112:113], v44 offset0:181 offset1:189
	ds_read2_b32 v[114:115], v44 offset0:214 offset1:222
	ds_read2_b32 v[116:117], v44 offset0:247 offset1:255
	v_or_b32_e32 v2, v98, v93
	v_mul_u32_u24_e32 v2, 0xc00, v2
	v_lshlrev_b32_e32 v2, 1, v2
	v_lshl_add_u64 v[118:119], v[100:101], 0, v[2:3]
	v_or_b32_e32 v2, v98, v94
	v_mul_u32_u24_e32 v2, 0xc00, v2
	s_waitcnt lgkmcnt(6)
	v_cvt_pk_bf16_f32 v28, v102, v104
	s_waitcnt lgkmcnt(4)
	v_cvt_pk_bf16_f32 v29, v106, v108
	s_waitcnt lgkmcnt(2)
	v_cvt_pk_bf16_f32 v30, v110, v112
	s_waitcnt lgkmcnt(0)
	v_cvt_pk_bf16_f32 v31, v114, v116
	v_lshlrev_b32_e32 v2, 1, v2
	global_store_dwordx4 v[118:119], v[28:31], off
	v_lshl_add_u64 v[98:99], v[100:101], 0, v[2:3]
	s_nop 0
	v_cvt_pk_bf16_f32 v28, v103, v105
	v_cvt_pk_bf16_f32 v29, v107, v109
	v_cvt_pk_bf16_f32 v30, v111, v113
	v_cvt_pk_bf16_f32 v31, v115, v117
	global_store_dwordx4 v[98:99], v[28:31], off
	s_waitcnt lgkmcnt(0)

.LBB0_537:
	s_andn2_saveexec_b64 s[44:45], s[38:39]
	s_cbranch_execz .LBB0_604
	v_and_b32_e32 v2, 0x3fc0, v96
	v_add_u32_e32 v2, 0xffffdd00, v2
	v_and_b32_e32 v98, 0x3e0, v95
	v_lshlrev_b32_e32 v28, 2, v98
	v_mov_b32_e32 v29, v3
	v_or_b32_e32 v30, v2, v32
	v_mov_b32_e32 v31, v3
	v_lshl_add_u64 v[28:29], v[24:25], 0, v[28:29]
	v_lshlrev_b64 v[100:101], 12, v[30:31]
	v_lshl_add_u64 v[100:101], v[28:29], 0, v[100:101]
	s_mov_b64 s[0:1], 0x2000
	global_load_dword v120, v[100:101], off nt
	v_lshl_add_u64 v[100:101], v[100:101], 0, s[0:1]
	global_load_dword v121, v[100:101], off nt
	v_lshl_add_u64 v[100:101], v[100:101], 0, s[0:1]
	global_load_dword v122, v[100:101], off nt
	v_lshl_add_u64 v[100:101], v[100:101], 0, s[0:1]
	global_load_dword v123, v[100:101], off nt
	v_lshl_add_u64 v[100:101], v[100:101], 0, s[0:1]
	global_load_dword v124, v[100:101], off nt
	v_lshl_add_u64 v[100:101], v[100:101], 0, s[0:1]
	global_load_dword v125, v[100:101], off nt
	v_lshl_add_u64 v[100:101], v[100:101], 0, s[0:1]
	global_load_dword v126, v[100:101], off nt
	v_lshl_add_u64 v[100:101], v[100:101], 0, s[0:1]
	global_load_dword v127, v[100:101], off nt
	v_lshl_add_u64 v[100:101], v[100:101], 0, s[0:1]
	global_load_dword v128, v[100:101], off nt
	v_lshl_add_u64 v[100:101], v[100:101], 0, s[0:1]
	global_load_dword v129, v[100:101], off nt
	v_lshl_add_u64 v[100:101], v[100:101], 0, s[0:1]
	global_load_dword v130, v[100:101], off nt
	v_lshl_add_u64 v[100:101], v[100:101], 0, s[0:1]
	global_load_dword v131, v[100:101], off nt
	v_lshl_add_u64 v[100:101], v[100:101], 0, s[0:1]
	global_load_dword v132, v[100:101], off nt
	v_lshl_add_u64 v[100:101], v[100:101], 0, s[0:1]
	global_load_dword v133, v[100:101], off nt
	v_lshl_add_u64 v[100:101], v[100:101], 0, s[0:1]
	global_load_dword v134, v[100:101], off nt
	v_lshl_add_u64 v[100:101], v[100:101], 0, s[0:1]
	global_load_dword v135, v[100:101], off nt
	v_lshl_add_u64 v[100:101], v[100:101], 0, s[0:1]
	global_load_dword v136, v[100:101], off nt
	v_lshl_add_u64 v[100:101], v[100:101], 0, s[0:1]
	global_load_dword v137, v[100:101], off nt
	v_lshl_add_u64 v[100:101], v[100:101], 0, s[0:1]
	global_load_dword v138, v[100:101], off nt
	v_lshl_add_u64 v[100:101], v[100:101], 0, s[0:1]
	global_load_dword v139, v[100:101], off nt
	v_lshl_add_u64 v[100:101], v[100:101], 0, s[0:1]
	global_load_dword v140, v[100:101], off nt
	v_lshl_add_u64 v[100:101], v[100:101], 0, s[0:1]
	global_load_dword v141, v[100:101], off nt
	v_lshl_add_u64 v[100:101], v[100:101], 0, s[0:1]
	global_load_dword v142, v[100:101], off nt
	v_lshl_add_u64 v[100:101], v[100:101], 0, s[0:1]
	global_load_dword v143, v[100:101], off nt
	v_lshl_add_u64 v[100:101], v[100:101], 0, s[0:1]
	global_load_dword v144, v[100:101], off nt
	v_lshl_add_u64 v[100:101], v[100:101], 0, s[0:1]
	global_load_dword v145, v[100:101], off nt
	v_lshl_add_u64 v[100:101], v[100:101], 0, s[0:1]
	global_load_dword v146, v[100:101], off nt
	v_lshl_add_u64 v[100:101], v[100:101], 0, s[0:1]
	global_load_dword v147, v[100:101], off nt
	v_lshl_add_u64 v[100:101], v[100:101], 0, s[0:1]
	global_load_dword v148, v[100:101], off nt
	v_lshl_add_u64 v[100:101], v[100:101], 0, s[0:1]
	global_load_dword v149, v[100:101], off nt
	v_lshl_add_u64 v[100:101], v[100:101], 0, s[0:1]
	global_load_dword v150, v[100:101], off nt
	v_lshl_add_u64 v[100:101], v[100:101], 0, s[0:1]
	global_load_dword v151, v[100:101], off nt
	v_readlane_b32 s4, v253, 8
	v_readlane_b32 s5, v253, 9
	v_readlane_b32 s2, v252, 58
	v_readlane_b32 s3, v252, 59
	v_add_u32_e32 v99, v33, v34
	s_and_b64 vcc, exec, s[4:5]
	s_cbranch_vccz .Ltrks_noscale
	v_lshl_add_u64 v[30:31], v[30:31], 2, s[2:3]
	global_load_dword v152, v[30:31], off offset:0
	global_load_dword v153, v[30:31], off offset:8
	global_load_dword v154, v[30:31], off offset:16
	global_load_dword v155, v[30:31], off offset:24
	global_load_dword v156, v[30:31], off offset:32
	global_load_dword v157, v[30:31], off offset:40
	global_load_dword v158, v[30:31], off offset:48
	global_load_dword v159, v[30:31], off offset:56
	global_load_dword v160, v[30:31], off offset:64
	global_load_dword v161, v[30:31], off offset:72
	global_load_dword v162, v[30:31], off offset:80
	global_load_dword v163, v[30:31], off offset:88
	global_load_dword v164, v[30:31], off offset:96
	global_load_dword v165, v[30:31], off offset:104
	global_load_dword v166, v[30:31], off offset:112
	global_load_dword v167, v[30:31], off offset:120
	global_load_dword v168, v[30:31], off offset:128
	global_load_dword v169, v[30:31], off offset:136
	global_load_dword v170, v[30:31], off offset:144
	global_load_dword v171, v[30:31], off offset:152
	global_load_dword v172, v[30:31], off offset:160
	global_load_dword v173, v[30:31], off offset:168
	global_load_dword v174, v[30:31], off offset:176
	global_load_dword v175, v[30:31], off offset:184
	global_load_dword v176, v[30:31], off offset:192
	global_load_dword v177, v[30:31], off offset:200
	global_load_dword v178, v[30:31], off offset:208
	global_load_dword v179, v[30:31], off offset:216
	global_load_dword v180, v[30:31], off offset:224
	global_load_dword v181, v[30:31], off offset:232
	global_load_dword v182, v[30:31], off offset:240
	global_load_dword v183, v[30:31], off offset:248
	s_waitcnt vmcnt(31)
	v_mul_f32_e32 v120, v120, v152
	ds_write_b32 v99, v120 offset:0
	s_waitcnt vmcnt(30)
	v_mul_f32_e32 v121, v121, v153
	ds_write_b32 v99, v121 offset:264
	s_waitcnt vmcnt(29)
	v_mul_f32_e32 v122, v122, v154
	ds_write_b32 v99, v122 offset:528
	s_waitcnt vmcnt(28)
	v_mul_f32_e32 v123, v123, v155
	ds_write_b32 v99, v123 offset:792
	s_waitcnt vmcnt(27)
	v_mul_f32_e32 v124, v124, v156
	ds_write_b32 v99, v124 offset:1056
	s_waitcnt vmcnt(26)
	v_mul_f32_e32 v125, v125, v157
	ds_write_b32 v99, v125 offset:1320
	s_waitcnt vmcnt(25)
	v_mul_f32_e32 v126, v126, v158
	ds_write_b32 v99, v126 offset:1584
	s_waitcnt vmcnt(24)
	v_mul_f32_e32 v127, v127, v159
	ds_write_b32 v99, v127 offset:1848
	s_waitcnt vmcnt(23)
	v_mul_f32_e32 v128, v128, v160
	ds_write_b32 v99, v128 offset:2112
	s_waitcnt vmcnt(22)
	v_mul_f32_e32 v129, v129, v161
	ds_write_b32 v99, v129 offset:2376
	s_waitcnt vmcnt(21)
	v_mul_f32_e32 v130, v130, v162
	ds_write_b32 v99, v130 offset:2640
	s_waitcnt vmcnt(20)
	v_mul_f32_e32 v131, v131, v163
	ds_write_b32 v99, v131 offset:2904
	s_waitcnt vmcnt(19)
	v_mul_f32_e32 v132, v132, v164
	ds_write_b32 v99, v132 offset:3168
	s_waitcnt vmcnt(18)
	v_mul_f32_e32 v133, v133, v165
	ds_write_b32 v99, v133 offset:3432
	s_waitcnt vmcnt(17)
	v_mul_f32_e32 v134, v134, v166
	ds_write_b32 v99, v134 offset:3696
	s_waitcnt vmcnt(16)
	v_mul_f32_e32 v135, v135, v167
	ds_write_b32 v99, v135 offset:3960
	s_waitcnt vmcnt(15)
	v_mul_f32_e32 v136, v136, v168
	ds_write_b32 v99, v136 offset:4224
	s_waitcnt vmcnt(14)
	v_mul_f32_e32 v137, v137, v169
	ds_write_b32 v99, v137 offset:4488
	s_waitcnt vmcnt(13)
	v_mul_f32_e32 v138, v138, v170
	ds_write_b32 v99, v138 offset:4752
	s_waitcnt vmcnt(12)
	v_mul_f32_e32 v139, v139, v171
	ds_write_b32 v99, v139 offset:5016
	s_waitcnt vmcnt(11)
	v_mul_f32_e32 v140, v140, v172
	ds_write_b32 v99, v140 offset:5280
	s_waitcnt vmcnt(10)
	v_mul_f32_e32 v141, v141, v173
	ds_write_b32 v99, v141 offset:5544
	s_waitcnt vmcnt(9)
	v_mul_f32_e32 v142, v142, v174
	ds_write_b32 v99, v142 offset:5808
	s_waitcnt vmcnt(8)
	v_mul_f32_e32 v143, v143, v175
	ds_write_b32 v99, v143 offset:6072
	s_waitcnt vmcnt(7)
	v_mul_f32_e32 v144, v144, v176
	ds_write_b32 v99, v144 offset:6336
	s_waitcnt vmcnt(6)
	v_mul_f32_e32 v145, v145, v177
	ds_write_b32 v99, v145 offset:6600
	s_waitcnt vmcnt(5)
	v_mul_f32_e32 v146, v146, v178
	ds_write_b32 v99, v146 offset:6864
	s_waitcnt vmcnt(4)
	v_mul_f32_e32 v147, v147, v179
	ds_write_b32 v99, v147 offset:7128
	s_waitcnt vmcnt(3)
	v_mul_f32_e32 v148, v148, v180
	ds_write_b32 v99, v148 offset:7392
	s_waitcnt vmcnt(2)
	v_mul_f32_e32 v149, v149, v181
	ds_write_b32 v99, v149 offset:7656
	s_waitcnt vmcnt(1)
	v_mul_f32_e32 v150, v150, v182
	ds_write_b32 v99, v150 offset:7920
	s_waitcnt vmcnt(0)
	v_mul_f32_e32 v151, v151, v183
	ds_write_b32 v99, v151 offset:8184
	s_branch .Ltrks_join
.Ltrks_noscale:
	s_waitcnt vmcnt(31)
	ds_write_b32 v99, v120 offset:0
	s_waitcnt vmcnt(30)
	ds_write_b32 v99, v121 offset:264
	s_waitcnt vmcnt(29)
	ds_write_b32 v99, v122 offset:528
	s_waitcnt vmcnt(28)
	ds_write_b32 v99, v123 offset:792
	s_waitcnt vmcnt(27)
	ds_write_b32 v99, v124 offset:1056
	s_waitcnt vmcnt(26)
	ds_write_b32 v99, v125 offset:1320
	s_waitcnt vmcnt(25)
	ds_write_b32 v99, v126 offset:1584
	s_waitcnt vmcnt(24)
	ds_write_b32 v99, v127 offset:1848
	s_waitcnt vmcnt(23)
	ds_write_b32 v99, v128 offset:2112
	s_waitcnt vmcnt(22)
	ds_write_b32 v99, v129 offset:2376
	s_waitcnt vmcnt(21)
	ds_write_b32 v99, v130 offset:2640
	s_waitcnt vmcnt(20)
	ds_write_b32 v99, v131 offset:2904
	s_waitcnt vmcnt(19)
	ds_write_b32 v99, v132 offset:3168
	s_waitcnt vmcnt(18)
	ds_write_b32 v99, v133 offset:3432
	s_waitcnt vmcnt(17)
	ds_write_b32 v99, v134 offset:3696
	s_waitcnt vmcnt(16)
	ds_write_b32 v99, v135 offset:3960
	s_waitcnt vmcnt(15)
	ds_write_b32 v99, v136 offset:4224
	s_waitcnt vmcnt(14)
	ds_write_b32 v99, v137 offset:4488
	s_waitcnt vmcnt(13)
	ds_write_b32 v99, v138 offset:4752
	s_waitcnt vmcnt(12)
	ds_write_b32 v99, v139 offset:5016
	s_waitcnt vmcnt(11)
	ds_write_b32 v99, v140 offset:5280
	s_waitcnt vmcnt(10)
	ds_write_b32 v99, v141 offset:5544
	s_waitcnt vmcnt(9)
	ds_write_b32 v99, v142 offset:5808
	s_waitcnt vmcnt(8)
	ds_write_b32 v99, v143 offset:6072
	s_waitcnt vmcnt(7)
	ds_write_b32 v99, v144 offset:6336
	s_waitcnt vmcnt(6)
	ds_write_b32 v99, v145 offset:6600
	s_waitcnt vmcnt(5)
	ds_write_b32 v99, v146 offset:6864
	s_waitcnt vmcnt(4)
	ds_write_b32 v99, v147 offset:7128
	s_waitcnt vmcnt(3)
	ds_write_b32 v99, v148 offset:7392
	s_waitcnt vmcnt(2)
	ds_write_b32 v99, v149 offset:7656
	s_waitcnt vmcnt(1)
	ds_write_b32 v99, v150 offset:7920
	s_waitcnt vmcnt(0)
	ds_write_b32 v99, v151 offset:8184
.Ltrks_join:
	v_readlane_b32 s0, v252, 56
	v_readlane_b32 s2, v252, 58
	v_readlane_b32 s3, v252, 59
	v_readlane_b32 s4, v252, 60
	v_readlane_b32 s5, v252, 61
	v_readlane_b32 s6, v252, 62
	v_readlane_b32 s7, v252, 63
	v_readlane_b32 s8, v253, 0
	v_readlane_b32 s9, v253, 1
	v_readlane_b32 s10, v253, 2
	v_readlane_b32 s11, v253, 3
	v_readlane_b32 s12, v253, 4
	v_readlane_b32 s13, v253, 5
	v_readlane_b32 s14, v253, 6
	v_readlane_b32 s15, v253, 7
	s_mov_b32 s1, 0x8880
	s_waitcnt lgkmcnt(0)
	v_lshl_add_u64 v[100:101], v[2:3], 1, v[12:13]
	ds_read2_b32 v[102:103], v44 offset0:33 offset1:41
	ds_read2_b32 v[104:105], v44 offset1:8
	ds_read2_b32 v[106:107], v44 offset0:66 offset1:74
	ds_read2_b32 v[108:109], v44 offset0:99 offset1:107
	ds_read2_b32 v[110:111], v44 offset0:132 offset1:140
	ds_read2_b32 v[112:113], v44 offset0:165 offset1:173
	ds_read2_b32 v[114:115], v44 offset0:198 offset1:206
	ds_read2_b32 v[116:117], v44 offset0:231 offset1:239
	v_or_b32_e32 v2, v98, v43
	v_mul_u32_u24_e32 v2, 0xc00, v2
	v_lshlrev_b32_e32 v2, 1, v2
	v_lshl_add_u64 v[118:119], v[100:101], 0, v[2:3]
	v_or_b32_e32 v2, v98, v92
	v_mul_u32_u24_e32 v2, 0xc00, v2
	s_waitcnt vmcnt(0) lgkmcnt(6)
	v_cvt_pk_bf16_f32 v28, v104, v102
	s_waitcnt lgkmcnt(4)
	v_cvt_pk_bf16_f32 v29, v106, v108
	s_waitcnt lgkmcnt(2)
	v_cvt_pk_bf16_f32 v30, v110, v112
	s_waitcnt lgkmcnt(0)
	v_cvt_pk_bf16_f32 v31, v114, v116
	v_lshlrev_b32_e32 v2, 1, v2
	global_store_dwordx4 v[118:119], v[28:31], off
	s_nop 1
	v_cvt_pk_bf16_f32 v28, v105, v103
	v_cvt_pk_bf16_f32 v29, v107, v109
	v_cvt_pk_bf16_f32 v30, v111, v113
	v_cvt_pk_bf16_f32 v31, v115, v117
	v_lshl_add_u64 v[102:103], v[100:101], 0, v[2:3]
	global_store_dwordx4 v[102:103], v[28:31], off
	ds_read2_b32 v[102:103], v44 offset0:16 offset1:24
	ds_read2_b32 v[104:105], v44 offset0:49 offset1:57
	ds_read2_b32 v[106:107], v44 offset0:82 offset1:90
	ds_read2_b32 v[108:109], v44 offset0:115 offset1:123
	ds_read2_b32 v[110:111], v44 offset0:148 offset1:156
	ds_read2_b32 v[112:113], v44 offset0:181 offset1:189
	ds_read2_b32 v[114:115], v44 offset0:214 offset1:222
	ds_read2_b32 v[116:117], v44 offset0:247 offset1:255
	v_or_b32_e32 v2, v98, v93
	v_mul_u32_u24_e32 v2, 0xc00, v2
	v_lshlrev_b32_e32 v2, 1, v2
	v_lshl_add_u64 v[118:119], v[100:101], 0, v[2:3]
	v_or_b32_e32 v2, v98, v94
	v_mul_u32_u24_e32 v2, 0xc00, v2
	s_waitcnt lgkmcnt(6)
	v_cvt_pk_bf16_f32 v28, v102, v104
	s_waitcnt lgkmcnt(4)
	v_cvt_pk_bf16_f32 v29, v106, v108
	s_waitcnt lgkmcnt(2)
	v_cvt_pk_bf16_f32 v30, v110, v112
	s_waitcnt lgkmcnt(0)
	v_cvt_pk_bf16_f32 v31, v114, v116
	v_lshlrev_b32_e32 v2, 1, v2
	global_store_dwordx4 v[118:119], v[28:31], off
	v_lshl_add_u64 v[98:99], v[100:101], 0, v[2:3]
	s_nop 0
	v_cvt_pk_bf16_f32 v28, v103, v105
	v_cvt_pk_bf16_f32 v29, v107, v109
	v_cvt_pk_bf16_f32 v30, v111, v113
	v_cvt_pk_bf16_f32 v31, v115, v117
	global_store_dwordx4 v[98:99], v[28:31], off
	s_waitcnt lgkmcnt(0)

.LBB0_605:
	s_andn2_saveexec_b64 s[38:39], s[42:43]
	s_cbranch_execz .LBB0_521
	s_mov_b32 s20, 0xea0ea0eb
	v_mul_hi_i32 v2, v97, s20
	v_add_u32_e32 v2, v2, v97
	v_lshrrev_b32_e32 v28, 31, v2
	v_ashrrev_i32_e32 v2, 8, v2
	v_add_u32_e32 v28, v2, v28
	v_mul_i32_i24_e32 v2, 0x118, v28
	v_sub_u32_e32 v29, v97, v2
	s_movk_i32 s0, 0x110
	v_add_u32_e32 v30, 1, v29
	v_cmp_gt_i32_e32 vcc, s0, v29
	v_mov_b32_e32 v31, 0xa0
	s_movk_i32 s20, 0xa0
	v_cndmask_b32_e32 v30, v31, v30, vcc
	v_cmp_gt_i32_e32 vcc, s20, v29
	s_movk_i32 s20, 0x111
	v_lshlrev_b32_e32 v28, 6, v28
	v_cndmask_b32_e32 v30, v30, v29, vcc
	v_lshlrev_b32_e32 v30, 5, v30
	v_ashrrev_i32_e32 v31, 31, v30
	v_cmp_gt_i32_e32 vcc, s20, v29
	v_lshl_add_u64 v[30:31], v[30:31], 2, v[26:27]
	v_add_u32_e32 v29, v33, v34
	s_cbranch_vccz .Ltrin_zero
	v_or_b32_e32 v98, v28, v32
	v_mad_i64_i32 v[100:101], s[20:21], v98, s1, v[30:31]
	s_mov_b64 s[20:21], 0x11100
	global_load_dword v120, v[100:101], off nt
	v_lshl_add_u64 v[100:101], v[100:101], 0, s[20:21]
	global_load_dword v121, v[100:101], off nt
	v_lshl_add_u64 v[100:101], v[100:101], 0, s[20:21]
	global_load_dword v122, v[100:101], off nt
	v_lshl_add_u64 v[100:101], v[100:101], 0, s[20:21]
	global_load_dword v123, v[100:101], off nt
	v_lshl_add_u64 v[100:101], v[100:101], 0, s[20:21]
	global_load_dword v124, v[100:101], off nt
	v_lshl_add_u64 v[100:101], v[100:101], 0, s[20:21]
	global_load_dword v125, v[100:101], off nt
	v_lshl_add_u64 v[100:101], v[100:101], 0, s[20:21]
	global_load_dword v126, v[100:101], off nt
	v_lshl_add_u64 v[100:101], v[100:101], 0, s[20:21]
	global_load_dword v127, v[100:101], off nt
	v_lshl_add_u64 v[100:101], v[100:101], 0, s[20:21]
	global_load_dword v128, v[100:101], off nt
	v_lshl_add_u64 v[100:101], v[100:101], 0, s[20:21]
	global_load_dword v129, v[100:101], off nt
	v_lshl_add_u64 v[100:101], v[100:101], 0, s[20:21]
	global_load_dword v130, v[100:101], off nt
	v_lshl_add_u64 v[100:101], v[100:101], 0, s[20:21]
	global_load_dword v131, v[100:101], off nt
	v_lshl_add_u64 v[100:101], v[100:101], 0, s[20:21]
	global_load_dword v132, v[100:101], off nt
	v_lshl_add_u64 v[100:101], v[100:101], 0, s[20:21]
	global_load_dword v133, v[100:101], off nt
	v_lshl_add_u64 v[100:101], v[100:101], 0, s[20:21]
	global_load_dword v134, v[100:101], off nt
	v_lshl_add_u64 v[100:101], v[100:101], 0, s[20:21]
	global_load_dword v135, v[100:101], off nt
	v_lshl_add_u64 v[100:101], v[100:101], 0, s[20:21]
	global_load_dword v136, v[100:101], off nt
	v_lshl_add_u64 v[100:101], v[100:101], 0, s[20:21]
	global_load_dword v137, v[100:101], off nt
	v_lshl_add_u64 v[100:101], v[100:101], 0, s[20:21]
	global_load_dword v138, v[100:101], off nt
	v_lshl_add_u64 v[100:101], v[100:101], 0, s[20:21]
	global_load_dword v139, v[100:101], off nt
	v_lshl_add_u64 v[100:101], v[100:101], 0, s[20:21]
	global_load_dword v140, v[100:101], off nt
	v_lshl_add_u64 v[100:101], v[100:101], 0, s[20:21]
	global_load_dword v141, v[100:101], off nt
	v_lshl_add_u64 v[100:101], v[100:101], 0, s[20:21]
	global_load_dword v142, v[100:101], off nt
	v_lshl_add_u64 v[100:101], v[100:101], 0, s[20:21]
	global_load_dword v143, v[100:101], off nt
	v_lshl_add_u64 v[100:101], v[100:101], 0, s[20:21]
	global_load_dword v144, v[100:101], off nt
	v_lshl_add_u64 v[100:101], v[100:101], 0, s[20:21]
	global_load_dword v145, v[100:101], off nt
	v_lshl_add_u64 v[100:101], v[100:101], 0, s[20:21]
	global_load_dword v146, v[100:101], off nt
	v_lshl_add_u64 v[100:101], v[100:101], 0, s[20:21]
	global_load_dword v147, v[100:101], off nt
	v_lshl_add_u64 v[100:101], v[100:101], 0, s[20:21]
	global_load_dword v148, v[100:101], off nt
	v_lshl_add_u64 v[100:101], v[100:101], 0, s[20:21]
	global_load_dword v149, v[100:101], off nt
	v_lshl_add_u64 v[100:101], v[100:101], 0, s[20:21]
	global_load_dword v150, v[100:101], off nt
	v_lshl_add_u64 v[100:101], v[100:101], 0, s[20:21]
	global_load_dword v151, v[100:101], off nt
	s_waitcnt vmcnt(31)
	ds_write_b32 v29, v120 offset:0
	s_waitcnt vmcnt(30)
	ds_write_b32 v29, v121 offset:264
	s_waitcnt vmcnt(29)
	ds_write_b32 v29, v122 offset:528
	s_waitcnt vmcnt(28)
	ds_write_b32 v29, v123 offset:792
	s_waitcnt vmcnt(27)
	ds_write_b32 v29, v124 offset:1056
	s_waitcnt vmcnt(26)
	ds_write_b32 v29, v125 offset:1320
	s_waitcnt vmcnt(25)
	ds_write_b32 v29, v126 offset:1584
	s_waitcnt vmcnt(24)
	ds_write_b32 v29, v127 offset:1848
	s_waitcnt vmcnt(23)
	ds_write_b32 v29, v128 offset:2112
	s_waitcnt vmcnt(22)
	ds_write_b32 v29, v129 offset:2376
	s_waitcnt vmcnt(21)
	ds_write_b32 v29, v130 offset:2640
	s_waitcnt vmcnt(20)
	ds_write_b32 v29, v131 offset:2904
	s_waitcnt vmcnt(19)
	ds_write_b32 v29, v132 offset:3168
	s_waitcnt vmcnt(18)
	ds_write_b32 v29, v133 offset:3432
	s_waitcnt vmcnt(17)
	ds_write_b32 v29, v134 offset:3696
	s_waitcnt vmcnt(16)
	ds_write_b32 v29, v135 offset:3960
	s_waitcnt vmcnt(15)
	ds_write_b32 v29, v136 offset:4224
	s_waitcnt vmcnt(14)
	ds_write_b32 v29, v137 offset:4488
	s_waitcnt vmcnt(13)
	ds_write_b32 v29, v138 offset:4752
	s_waitcnt vmcnt(12)
	ds_write_b32 v29, v139 offset:5016
	s_waitcnt vmcnt(11)
	ds_write_b32 v29, v140 offset:5280
	s_waitcnt vmcnt(10)
	ds_write_b32 v29, v141 offset:5544
	s_waitcnt vmcnt(9)
	ds_write_b32 v29, v142 offset:5808
	s_waitcnt vmcnt(8)
	ds_write_b32 v29, v143 offset:6072
	s_waitcnt vmcnt(7)
	ds_write_b32 v29, v144 offset:6336
	s_waitcnt vmcnt(6)
	ds_write_b32 v29, v145 offset:6600
	s_waitcnt vmcnt(5)
	ds_write_b32 v29, v146 offset:6864
	s_waitcnt vmcnt(4)
	ds_write_b32 v29, v147 offset:7128
	s_waitcnt vmcnt(3)
	ds_write_b32 v29, v148 offset:7392
	s_waitcnt vmcnt(2)
	ds_write_b32 v29, v149 offset:7656
	s_waitcnt vmcnt(1)
	ds_write_b32 v29, v150 offset:7920
	s_waitcnt vmcnt(0)
	ds_write_b32 v29, v151 offset:8184
	s_branch .Ltrin_tail
.Ltrin_zero:
	ds_write_b32 v29, v3 offset:0
	ds_write_b32 v29, v3 offset:264
	ds_write_b32 v29, v3 offset:528
	ds_write_b32 v29, v3 offset:792
	ds_write_b32 v29, v3 offset:1056
	ds_write_b32 v29, v3 offset:1320
	ds_write_b32 v29, v3 offset:1584
	ds_write_b32 v29, v3 offset:1848
	ds_write_b32 v29, v3 offset:2112
	ds_write_b32 v29, v3 offset:2376
	ds_write_b32 v29, v3 offset:2640
	ds_write_b32 v29, v3 offset:2904
	ds_write_b32 v29, v3 offset:3168
	ds_write_b32 v29, v3 offset:3432
	ds_write_b32 v29, v3 offset:3696
	ds_write_b32 v29, v3 offset:3960
	ds_write_b32 v29, v3 offset:4224
	ds_write_b32 v29, v3 offset:4488
	ds_write_b32 v29, v3 offset:4752
	ds_write_b32 v29, v3 offset:5016
	ds_write_b32 v29, v3 offset:5280
	ds_write_b32 v29, v3 offset:5544
	ds_write_b32 v29, v3 offset:5808
	ds_write_b32 v29, v3 offset:6072
	ds_write_b32 v29, v3 offset:6336
	ds_write_b32 v29, v3 offset:6600
	ds_write_b32 v29, v3 offset:6864
	ds_write_b32 v29, v3 offset:7128
	ds_write_b32 v29, v3 offset:7392
	ds_write_b32 v29, v3 offset:7656
	ds_write_b32 v29, v3 offset:7920
	ds_write_b32 v29, v3 offset:8184
	s_branch .Ltrin_tail
